# pool tile fill: ten row loads per thread issued together (was load-wait-store per row)
# baseline (speedup 1.0000x reference)
.LBB0_802:
	s_and_b64 vcc, exec, s[0:1]
	s_cbranch_vccz .LBB0_819
	s_cmpk_gt_u32 s9, 0x53f
	v_readlane_b32 s2, v207, 0
	s_cselect_b64 s[0:1], -1, 0
	v_readlane_b32 s3, v207, 1
	s_and_b64 s[0:1], s[2:3], s[0:1]
	s_and_b64 vcc, exec, s[0:1]
	s_cbranch_vccnz .LBB0_819
	s_add_i32 s0, s9, 0xfffffbc0
	s_lshl_b32 s6, s0, 6
	s_cmpk_lt_u32 s0, 0x100
	s_cselect_b64 s[0:1], -1, 0
	s_and_b64 s[2:3], s[0:1], exec
	s_movk_i32 s2, 0x1000
	s_cselect_b32 s7, s2, 0x100
	s_movk_i32 s2, 0xc0
	s_cselect_b32 s2, 0xfc0, s2
	v_mov_b32_e32 v136, v133
	s_and_b32 s33, s2, s6
	s_movk_i32 s2, 0xa00
	s_nop 0
	v_cmp_gt_i32_e32 vcc, s2, v136
	s_and_saveexec_b64 s[2:3], vcc
	s_cbranch_execz .LBB0_809
	s_and_b64 s[0:1], s[0:1], exec
	s_movk_i32 s0, 0x7f00
	s_cselect_b32 s0, 0x3000, s0
	s_and_b32 s10, s0, s6
	s_add_i32 s34, s33, -8
	v_readlane_b32 s48, v210, 62
	v_readlane_b32 s49, v210, 63
	v_ashrrev_i32_e32 v4, 5, v136
	v_and_b32_e32 v0, 31, v136
	v_lshlrev_b32_e32 v0, 4, v0
	v_lshl_or_b32 v5, v4, 9, v0
	s_add_i32 s0, s7, -1
	v_mov_b64_e32 v[48:49], s[48:49]
	s_add_i32 s1, s34, 0
	v_add_u32_e32 v6, s1, v4
	v_max_i32_e32 v6, 0, v6
	v_min_i32_e32 v6, s0, v6
	v_add_u32_e32 v6, s10, v6
	v_mad_u64_u32 v[50:51], s[38:39], v6, s68, v[48:49]
	v_lshl_add_u64 v[50:51], v[50:51], 0, v[0:1]
	global_load_dwordx4 v[8:11], v[50:51], off offset:2560
	s_add_i32 s1, s34, 8
	v_add_u32_e32 v6, s1, v4
	v_max_i32_e32 v6, 0, v6
	v_min_i32_e32 v6, s0, v6
	v_add_u32_e32 v6, s10, v6
	v_mad_u64_u32 v[50:51], s[38:39], v6, s68, v[48:49]
	v_lshl_add_u64 v[50:51], v[50:51], 0, v[0:1]
	global_load_dwordx4 v[12:15], v[50:51], off offset:2560
	s_add_i32 s1, s34, 16
	v_add_u32_e32 v6, s1, v4
	v_max_i32_e32 v6, 0, v6
	v_min_i32_e32 v6, s0, v6
	v_add_u32_e32 v6, s10, v6
	v_mad_u64_u32 v[50:51], s[38:39], v6, s68, v[48:49]
	v_lshl_add_u64 v[50:51], v[50:51], 0, v[0:1]
	global_load_dwordx4 v[16:19], v[50:51], off offset:2560
	s_add_i32 s1, s34, 24
	v_add_u32_e32 v6, s1, v4
	v_max_i32_e32 v6, 0, v6
	v_min_i32_e32 v6, s0, v6
	v_add_u32_e32 v6, s10, v6
	v_mad_u64_u32 v[50:51], s[38:39], v6, s68, v[48:49]
	v_lshl_add_u64 v[50:51], v[50:51], 0, v[0:1]
	global_load_dwordx4 v[20:23], v[50:51], off offset:2560
	s_add_i32 s1, s34, 32
	v_add_u32_e32 v6, s1, v4
	v_max_i32_e32 v6, 0, v6
	v_min_i32_e32 v6, s0, v6
	v_add_u32_e32 v6, s10, v6
	v_mad_u64_u32 v[50:51], s[38:39], v6, s68, v[48:49]
	v_lshl_add_u64 v[50:51], v[50:51], 0, v[0:1]
	global_load_dwordx4 v[24:27], v[50:51], off offset:2560
	s_add_i32 s1, s34, 40
	v_add_u32_e32 v6, s1, v4
	v_max_i32_e32 v6, 0, v6
	v_min_i32_e32 v6, s0, v6
	v_add_u32_e32 v6, s10, v6
	v_mad_u64_u32 v[50:51], s[38:39], v6, s68, v[48:49]
	v_lshl_add_u64 v[50:51], v[50:51], 0, v[0:1]
	global_load_dwordx4 v[28:31], v[50:51], off offset:2560
	s_add_i32 s1, s34, 48
	v_add_u32_e32 v6, s1, v4
	v_max_i32_e32 v6, 0, v6
	v_min_i32_e32 v6, s0, v6
	v_add_u32_e32 v6, s10, v6
	v_mad_u64_u32 v[50:51], s[38:39], v6, s68, v[48:49]
	v_lshl_add_u64 v[50:51], v[50:51], 0, v[0:1]
	global_load_dwordx4 v[32:35], v[50:51], off offset:2560
	s_add_i32 s1, s34, 56
	v_add_u32_e32 v6, s1, v4
	v_max_i32_e32 v6, 0, v6
	v_min_i32_e32 v6, s0, v6
	v_add_u32_e32 v6, s10, v6
	v_mad_u64_u32 v[50:51], s[38:39], v6, s68, v[48:49]
	v_lshl_add_u64 v[50:51], v[50:51], 0, v[0:1]
	global_load_dwordx4 v[36:39], v[50:51], off offset:2560
	s_add_i32 s1, s34, 64
	v_add_u32_e32 v6, s1, v4
	v_max_i32_e32 v6, 0, v6
	v_min_i32_e32 v6, s0, v6
	v_add_u32_e32 v6, s10, v6
	v_mad_u64_u32 v[50:51], s[38:39], v6, s68, v[48:49]
	v_lshl_add_u64 v[50:51], v[50:51], 0, v[0:1]
	global_load_dwordx4 v[40:43], v[50:51], off offset:2560
	s_add_i32 s1, s34, 72
	v_add_u32_e32 v6, s1, v4
	v_max_i32_e32 v6, 0, v6
	v_min_i32_e32 v6, s0, v6
	v_add_u32_e32 v6, s10, v6
	v_mad_u64_u32 v[50:51], s[38:39], v6, s68, v[48:49]
	v_lshl_add_u64 v[50:51], v[50:51], 0, v[0:1]
	global_load_dwordx4 v[44:47], v[50:51], off offset:2560
	s_waitcnt vmcnt(0)
	ds_write_b128 v5, v[8:11]
	ds_write_b128 v5, v[12:15] offset:4096
	ds_write_b128 v5, v[16:19] offset:8192
	ds_write_b128 v5, v[20:23] offset:12288
	ds_write_b128 v5, v[24:27] offset:16384
	ds_write_b128 v5, v[28:31] offset:20480
	ds_write_b128 v5, v[32:35] offset:24576
	ds_write_b128 v5, v[36:39] offset:28672
	ds_write_b128 v5, v[40:43] offset:32768
	ds_write_b128 v5, v[44:47] offset:36864
